# skip buffer_wbl2 in barrier leader when all participants share one XCC (nx==1)
# speedup vs baseline: 1.0031x; 1.0031x over previous
; __device__ __forceinline__ unsigned xb_add(unsigned* p, unsigned v) { return __hip_atomic_fetch_add(p, v, __ATOMIC_RELAXED, __HIP_MEMORY_SCOPE_AGENT); }
; __device__ __forceinline__ void xcd_barrier(const XcdBarrier& b) {
;     ...
;         const unsigned old = xb_add(&bar[XB_XSUB(b.x)], 1u);
;         const unsigned gen = old / nloc;
;         if (old + 1u == (gen + 1u) * nloc) {
;             __builtin_amdgcn_fence(__ATOMIC_RELEASE, "agent");
;             asm volatile("s_waitcnt vmcnt(0)" ::: "memory");
;             const unsigned og = xb_add(&bar[XB_TOP], 1u);
;             const unsigned tg = og / nx;
;             if (og + 1u == (tg + 1u) * nx) xb_add(&bar[XB_TOPGEN], 1u);
.LBB0_75:
	s_andn2_saveexec_b64 s[8:9], s[8:9]
	s_cbranch_execz .LBB0_95
	s_mov_b64 s[8:9], exec
	v_cmp_eq_u32_e32 vcc, 1, v0
	s_cbranch_vccnz .Lskip_wb_1
	buffer_wbl2 sc1
.Lskip_wb_1:
	s_waitcnt lgkmcnt(0)
	s_waitcnt vmcnt(0)
	v_mbcnt_lo_u32_b32 v1, s8, 0
	v_mbcnt_hi_u32_b32 v1, s9, v1
	v_cmp_eq_u32_e32 vcc, 0, v1
	s_and_saveexec_b64 s[12:13], vcc
	s_cbranch_execz .LBB0_78
	s_bcnt1_i32_b64 s3, s[8:9]
	v_mov_b32_e32 v2, 0x1fb53000
	v_mov_b32_e32 v3, s3
	global_atomic_add v2, v2, v3, s[16:17] offset:1024 sc0

; __device__ __forceinline__ unsigned xb_add(unsigned* p, unsigned v) { return __hip_atomic_fetch_add(p, v, __ATOMIC_RELAXED, __HIP_MEMORY_SCOPE_AGENT); }
; __device__ __forceinline__ void xcd_barrier(const XcdBarrier& b) {
;     ...
;         const unsigned old = xb_add(&bar[XB_XSUB(b.x)], 1u);
;         const unsigned gen = old / nloc;
;         if (old + 1u == (gen + 1u) * nloc) {
;             __builtin_amdgcn_fence(__ATOMIC_RELEASE, "agent");
;             asm volatile("s_waitcnt vmcnt(0)" ::: "memory");
;             const unsigned og = xb_add(&bar[XB_TOP], 1u);
;             const unsigned tg = og / nx;
;             if (og + 1u == (tg + 1u) * nx) xb_add(&bar[XB_TOPGEN], 1u);
.LBB0_173:
	s_andn2_saveexec_b64 s[10:11], s[12:13]
	s_cbranch_execz .LBB0_193
	s_mov_b64 s[12:13], exec
	v_cmp_eq_u32_e32 vcc, 1, v0
	s_cbranch_vccnz .Lskip_wb_2
	buffer_wbl2 sc1
.Lskip_wb_2:
	s_waitcnt lgkmcnt(0)
	s_waitcnt vmcnt(0)
	v_mbcnt_lo_u32_b32 v1, s12, 0
	v_mbcnt_hi_u32_b32 v1, s13, v1
	v_cmp_eq_u32_e32 vcc, 0, v1
	s_and_saveexec_b64 s[14:15], vcc
	s_cbranch_execz .LBB0_176
	s_bcnt1_i32_b64 s3, s[12:13]
	v_mov_b32_e32 v2, 0x7000
	v_mov_b32_e32 v3, s3
	global_atomic_add v2, v2, v3, s[68:69] offset:1024 sc0

; __device__ __forceinline__ unsigned xb_add(unsigned* p, unsigned v) { return __hip_atomic_fetch_add(p, v, __ATOMIC_RELAXED, __HIP_MEMORY_SCOPE_AGENT); }
; __device__ __forceinline__ void xcd_barrier(const XcdBarrier& b) {
;     ...
;             __builtin_amdgcn_fence(__ATOMIC_RELEASE, "agent");
;             asm volatile("s_waitcnt vmcnt(0)" ::: "memory");
;             const unsigned og = xb_add(&bar[XB_TOP], 1u);
.Lskip_wb_3:
	s_waitcnt lgkmcnt(0)
	s_waitcnt vmcnt(0)
	v_mbcnt_lo_u32_b32 v1, s8, 0
	v_mbcnt_hi_u32_b32 v1, s9, v1
	v_cmp_eq_u32_e32 vcc, 0, v1
	s_and_saveexec_b64 s[22:23], vcc
	s_cbranch_execz .LBB0_255
	s_bcnt1_i32_b64 s8, s[8:9]
	v_mov_b32_e32 v2, 0x3000
	v_mov_b32_e32 v3, s8
	global_atomic_add v2, v2, v3, s[18:19] offset:1024 sc0

; __device__ __forceinline__ unsigned xb_add(unsigned* p, unsigned v) { return __hip_atomic_fetch_add(p, v, __ATOMIC_RELAXED, __HIP_MEMORY_SCOPE_AGENT); }
; __device__ __forceinline__ void xcd_barrier(const XcdBarrier& b) {
;     ...
;             __builtin_amdgcn_fence(__ATOMIC_RELEASE, "agent");
;             asm volatile("s_waitcnt vmcnt(0)" ::: "memory");
;             const unsigned og = xb_add(&bar[XB_TOP], 1u);
.Lskip_wb_4:
	s_waitcnt lgkmcnt(0)
	s_waitcnt vmcnt(0)
	v_mbcnt_lo_u32_b32 v1, s8, 0
	v_mbcnt_hi_u32_b32 v1, s9, v1
	v_cmp_eq_u32_e32 vcc, 0, v1
	s_and_saveexec_b64 s[26:27], vcc
	s_cbranch_execz .LBB0_323
	s_bcnt1_i32_b64 s3, s[8:9]
	v_mov_b32_e32 v2, 0x3000
	v_mov_b32_e32 v3, s3
	global_atomic_add v2, v2, v3, s[18:19] offset:1024 sc0

; __device__ __forceinline__ unsigned xb_add(unsigned* p, unsigned v) { return __hip_atomic_fetch_add(p, v, __ATOMIC_RELAXED, __HIP_MEMORY_SCOPE_AGENT); }
; __device__ __forceinline__ void xcd_barrier(const XcdBarrier& b) {
;     ...
;             __builtin_amdgcn_fence(__ATOMIC_RELEASE, "agent");
;             asm volatile("s_waitcnt vmcnt(0)" ::: "memory");
;             const unsigned og = xb_add(&bar[XB_TOP], 1u);
.LBB0_379:
	s_andn2_saveexec_b64 s[6:7], s[6:7]
	s_cbranch_execz .LBB0_399
	s_mov_b64 s[6:7], exec
	v_cmp_eq_u32_e32 vcc, 1, v0
	s_cbranch_vccnz .Lskip_wb_5
	buffer_wbl2 sc1
.Lskip_wb_5:
	s_waitcnt lgkmcnt(0)
	s_waitcnt vmcnt(0)
	v_mbcnt_lo_u32_b32 v1, s6, 0
	v_mbcnt_hi_u32_b32 v1, s7, v1
	v_cmp_eq_u32_e32 vcc, 0, v1
	s_and_saveexec_b64 s[8:9], vcc
	s_cbranch_execz .LBB0_382
	s_bcnt1_i32_b64 s6, s[6:7]
	v_mov_b32_e32 v2, 0x3000
	v_mov_b32_e32 v3, s6
	global_atomic_add v2, v2, v3, s[18:19] offset:1024 sc0

; __device__ __forceinline__ unsigned xb_add(unsigned* p, unsigned v) { return __hip_atomic_fetch_add(p, v, __ATOMIC_RELAXED, __HIP_MEMORY_SCOPE_AGENT); }
; __device__ __forceinline__ void xcd_barrier(const XcdBarrier& b) {
;     ...
;             __builtin_amdgcn_fence(__ATOMIC_RELEASE, "agent");
;             asm volatile("s_waitcnt vmcnt(0)" ::: "memory");
;             const unsigned og = xb_add(&bar[XB_TOP], 1u);
.Lskip_wb_6:
	s_waitcnt lgkmcnt(0)
	s_waitcnt vmcnt(0)
	v_mbcnt_lo_u32_b32 v1, s6, 0
	v_mbcnt_hi_u32_b32 v1, s7, v1
	v_cmp_eq_u32_e32 vcc, 0, v1
	s_and_saveexec_b64 s[8:9], vcc
	s_cbranch_execz .LBB0_450
	s_bcnt1_i32_b64 s6, s[6:7]
	v_mov_b32_e32 v2, 0x7000
	v_mov_b32_e32 v3, s6
	global_atomic_add v2, v2, v3, s[68:69] offset:1024 sc0

; __device__ __forceinline__ unsigned xb_add(unsigned* p, unsigned v) { return __hip_atomic_fetch_add(p, v, __ATOMIC_RELAXED, __HIP_MEMORY_SCOPE_AGENT); }
; __device__ __forceinline__ void xcd_barrier(const XcdBarrier& b) {
;     ...
;             __builtin_amdgcn_fence(__ATOMIC_RELEASE, "agent");
;             asm volatile("s_waitcnt vmcnt(0)" ::: "memory");
;             const unsigned og = xb_add(&bar[XB_TOP], 1u);
.Lskip_wb_9:
	s_waitcnt lgkmcnt(0)
	s_waitcnt vmcnt(0)
	v_mbcnt_lo_u32_b32 v1, s8, 0
	v_mbcnt_hi_u32_b32 v1, s9, v1
	v_cmp_eq_u32_e32 vcc, 0, v1
	s_and_saveexec_b64 s[30:31], vcc
	s_cbranch_execz .LBB0_713
	s_bcnt1_i32_b64 s8, s[8:9]
	v_mov_b32_e32 v2, 0x3000
	v_mov_b32_e32 v3, s8
	global_atomic_add v2, v2, v3, s[18:19] offset:1024 sc0
